# attention unit start: 8 K/V tile loads + q loads issued together instead of one round trip each
# speedup vs baseline: 1.0034x; 1.0034x over previous
.LBB0_298:
	s_ashr_i32 s66, s98, 31
	s_lshr_b32 s66, s66, 25
	s_add_i32 s68, s98, s66
	s_and_b32 s66, s68, 0xffffff80
	s_sub_i32 s99, s98, s66
	s_mul_hi_i32 s66, s98, 0x2aaaaaab
	s_lshr_b32 s67, s66, 31
	s_ashr_i32 s66, s66, 6
	s_add_i32 s72, s66, s67
	s_ashr_i32 s73, s72, 31
	s_lshl_b32 s74, s99, 7
	s_lshl_b64 s[66:67], s[72:73], 14
	s_ashr_i32 s75, s74, 31
	s_add_u32 s66, s66, s74
	s_addc_u32 s67, s67, s75
	s_cmp_gt_i32 s99, 0
	s_cselect_b64 s[70:71], -1, 0
	s_add_u32 s76, s66, 0xffffff80
	s_addc_u32 s77, s67, -1
	s_ashr_i32 s68, s68, 7
	s_mul_hi_i32 s69, s68, 0x55555556
	s_lshr_b32 s73, s69, 31
	s_add_i32 s69, s69, s73
	s_mul_i32 s69, s69, 3
	s_sub_i32 s68, s68, s69
	s_lshl_b32 s84, s68, 7
	s_mul_i32 s86, s76, 0x2400
	s_mul_hi_i32 s87, s76, 0x2400
	s_add_u32 s86, s86, s84
	s_addc_u32 s87, s87, 0
	s_add_u32 s86, s86, s50
	s_addc_u32 s87, s87, s51
	v_mad_u32_u24 v250, v128, s95, v150
	v_mad_u32_u24 v254, v136, s95, v152
	v_add_u32_e32 v251, 0x90000, v250
	v_add_u32_e32 v252, 0x120000, v250
	v_add_u32_e32 v253, 0x1b0000, v250
	v_mov_b32_e32 v4, 0
	v_mov_b32_e32 v5, 0
	v_mov_b32_e32 v6, 0
	v_mov_b32_e32 v7, 0
	v_mov_b32_e32 v8, 0
	v_mov_b32_e32 v9, 0
	v_mov_b32_e32 v10, 0
	v_mov_b32_e32 v11, 0
	v_mov_b32_e32 v234, 0
	v_mov_b32_e32 v235, 0
	v_mov_b32_e32 v236, 0
	v_mov_b32_e32 v237, 0
	v_mov_b32_e32 v238, 0
	v_mov_b32_e32 v239, 0
	v_mov_b32_e32 v240, 0
	v_mov_b32_e32 v241, 0
	v_mov_b32_e32 v242, 0
	v_mov_b32_e32 v243, 0
	v_mov_b32_e32 v244, 0
	v_mov_b32_e32 v245, 0
	v_mov_b32_e32 v246, 0
	v_mov_b32_e32 v247, 0
	v_mov_b32_e32 v248, 0
	v_mov_b32_e32 v249, 0
	s_cmp_gt_i32 s99, 0
	s_cselect_b64 s[70:71], -1, 0
	s_or_b64 s[70:71], s[70:71], s[4:5]
	s_and_saveexec_b64 s[88:89], s[70:71]
	s_cbranch_execz .Lattn_stage_v_done
	global_load_dwordx4 v[234:237], v254, s[86:87] offset:3456
	global_load_dwordx4 v[238:241], v254, s[86:87] offset:3488
	global_load_dwordx4 v[242:245], v254, s[86:87] offset:3520
	global_load_dwordx4 v[246:249], v254, s[86:87] offset:3552
.Lattn_stage_v_done:
	s_mov_b64 exec, s[88:89]
	s_cmp_gt_i32 s99, 0
	s_cbranch_scc0 .Lattn_stage_k23
	global_load_dwordx4 v[4:7], v250, s[86:87] offset:3072
	global_load_dwordx4 v[8:11], v251, s[86:87] offset:3072
.Lattn_stage_k23:
	global_load_dwordx4 v[12:15], v252, s[86:87] offset:3072
	global_load_dwordx4 v[230:233], v253, s[86:87] offset:3072
	s_mov_b32 s69, 0
	s_lshl_b32 s70, s68, 3
	s_add_i32 s76, s70, s3
	v_or_b32_e32 v2, s66, v124
	v_mov_b64_e32 v[0:1], s[50:51]
	s_lshl_b32 s84, s76, 6
	v_mad_u64_u32 v[0:1], s[70:71], v2, s95, v[0:1]
	s_ashr_i32 s85, s84, 31
	v_mad_i32_i24 v1, s67, v187, v1
	s_lshl_b64 s[70:71], s[84:85], 1
	s_ashr_i32 s77, s76, 31
	v_lshl_add_u64 v[0:1], v[0:1], 0, s[70:71]
	v_lshlrev_b32_e32 v126, 1, v141
	s_lshl_b64 s[76:77], s[76:77], 2
	v_lshl_add_u64 v[0:1], v[0:1], 0, v[126:127]
	s_add_u32 s76, s78, s76
	global_load_dwordx4 v[48:51], v[0:1], off nt
	global_load_dwordx4 v[108:111], v[0:1], off offset:32 nt
	global_load_dwordx4 v[104:107], v[0:1], off offset:64 nt
	global_load_dwordx4 v[120:123], v[0:1], off offset:96 nt
	s_addc_u32 s77, s79, s77
	s_waitcnt vmcnt(5)
	ds_write_b128 v186, v[4:7]
	ds_write_b128 v176, v[8:11]
	ds_write_b128 v177, v[12:15]
	ds_write_b16 v179, v234 offset:36864
	ds_write_b16_d16_hi v179, v234 offset:37392
	ds_write_b16 v179, v235 offset:37920
	ds_write_b16_d16_hi v179, v235 offset:38448
	ds_write_b16 v179, v236 offset:38976
	ds_write_b16_d16_hi v179, v236 offset:39504
	ds_write_b16 v179, v237 offset:40032
	ds_write_b16_d16_hi v179, v237 offset:40560
	ds_write_b16 v180, v238 offset:36864
	ds_write_b16_d16_hi v180, v238 offset:37392
	ds_write_b16 v180, v239 offset:37920
	ds_write_b16_d16_hi v180, v239 offset:38448
	ds_write_b16 v180, v240 offset:38976
	ds_write_b16_d16_hi v180, v240 offset:39504
	ds_write_b16 v180, v241 offset:40032
	ds_write_b16_d16_hi v180, v241 offset:40560
	ds_write_b16 v181, v242 offset:36864
	ds_write_b16_d16_hi v181, v242 offset:37392
	ds_write_b16 v181, v243 offset:37920
	ds_write_b16_d16_hi v181, v243 offset:38448
	ds_write_b16 v181, v244 offset:38976
	ds_write_b16_d16_hi v181, v244 offset:39504
	ds_write_b16 v181, v245 offset:40032
	ds_write_b16_d16_hi v181, v245 offset:40560
	ds_write_b16 v182, v246 offset:36864
	ds_write_b16_d16_hi v182, v246 offset:37392
	ds_write_b16 v182, v247 offset:37920
	ds_write_b16_d16_hi v182, v247 offset:38448
	ds_write_b16 v182, v248 offset:38976
	ds_write_b16_d16_hi v182, v248 offset:39504
	ds_write_b16 v182, v249 offset:40032
	ds_write_b16_d16_hi v182, v249 offset:40560
	s_waitcnt vmcnt(4)
	ds_write_b128 v178, v[230:233]
	s_waitcnt lgkmcnt(0)
	s_barrier
	global_load_dword v4, v127, s[76:77]
	v_lshl_add_u64 v[0:1], s[84:85], 2, v[138:139]
	global_load_dwordx4 v[80:83], v[0:1], off
	global_load_dwordx4 v[84:87], v[0:1], off offset:16
	s_mul_i32 s85, s72, 0x9000000
	s_cmp_eq_u32 s99, 0
	s_mul_hi_i32 s84, s72, 0x9000000
	v_lshl_add_u64 v[0:1], v[124:125], 0, s[74:75]
	s_cselect_b64 s[72:73], -1, 0
	s_add_u32 s74, s70, s85
	s_addc_u32 s75, s71, s84
	v_mov_b64_e32 v[2:3], s[74:75]
	v_mad_u64_u32 v[2:3], s[74:75], v0, s95, v[2:3]
	v_mad_i32_i24 v3, v1, s95, v3
	v_mov_b32_e32 v151, v173
	v_mov_b32_e32 v153, v172
	s_mov_b32 s76, 0
	s_mov_b32 s77, 0
	v_lshl_add_u64 v[162:163], v[142:143], 0, s[70:71]
	v_lshl_add_u64 v[164:165], v[148:149], 0, v[2:3]
	s_waitcnt vmcnt(6)
	v_mov_b64_e32 v[90:91], v[50:51]
	s_waitcnt vmcnt(5)
	v_mov_b64_e32 v[92:93], v[108:109]
	s_waitcnt vmcnt(4)
	v_mov_b64_e32 v[96:97], v[104:105]
	s_waitcnt vmcnt(3)
	v_mov_b64_e32 v[100:101], v[120:121]
	v_mov_b64_e32 v[88:89], v[48:49]
	v_mov_b64_e32 v[94:95], v[110:111]
	v_mov_b64_e32 v[98:99], v[106:107]
	v_mov_b64_e32 v[102:103], v[122:123]
	s_waitcnt vmcnt(2)
	v_mul_f32_e32 v155, 0x3fb8aa3b, v4
	s_branch .LBB0_315

	.amdhsa_kernel _Z6mk_fwd4Args
		.amdhsa_group_segment_fixed_size 0
		.amdhsa_private_segment_fixed_size 0
		.amdhsa_kernarg_size 456
		.amdhsa_user_sgpr_count 2
		.amdhsa_user_sgpr_dispatch_ptr 0
		.amdhsa_user_sgpr_queue_ptr 0
		.amdhsa_user_sgpr_kernarg_segment_ptr 1
		.amdhsa_user_sgpr_dispatch_id 0
		.amdhsa_user_sgpr_kernarg_preload_length 0
		.amdhsa_user_sgpr_kernarg_preload_offset 0
		.amdhsa_user_sgpr_private_segment_size 0
		.amdhsa_uses_dynamic_stack 0
		.amdhsa_enable_private_segment 0
		.amdhsa_system_sgpr_workgroup_id_x 1
		.amdhsa_system_sgpr_workgroup_id_y 0
		.amdhsa_system_sgpr_workgroup_id_z 0
		.amdhsa_system_sgpr_workgroup_info 0
		.amdhsa_system_vgpr_workitem_id 2
		.amdhsa_next_free_vgpr 256
		.amdhsa_next_free_sgpr 100
		.amdhsa_accum_offset 256
		.amdhsa_reserve_vcc 1
		.amdhsa_float_round_mode_32 0
		.amdhsa_float_round_mode_16_64 0
		.amdhsa_float_denorm_mode_32 3
		.amdhsa_float_denorm_mode_16_64 3
		.amdhsa_dx10_clamp 1
		.amdhsa_ieee_mode 1
		.amdhsa_fp16_overflow 0
		.amdhsa_tg_split 0
		.amdhsa_exception_fp_ieee_invalid_op 0
		.amdhsa_exception_fp_denorm_src 0
		.amdhsa_exception_fp_ieee_div_zero 0
		.amdhsa_exception_fp_ieee_overflow 0
		.amdhsa_exception_fp_ieee_underflow 0
		.amdhsa_exception_fp_ieee_inexact 0
		.amdhsa_exception_int_div_zero 0
	.end_amdhsa_kernel

.Lfunc_end0:
	.size	_Z6mk_fwd4Args, .Lfunc_end0-_Z6mk_fwd4Args
	.set _Z6mk_fwd4Args.num_vgpr, 256
	.set _Z6mk_fwd4Args.num_agpr, 0
	.set _Z6mk_fwd4Args.numbered_sgpr, 100
	.set _Z6mk_fwd4Args.num_named_barrier, 0
	.set _Z6mk_fwd4Args.private_seg_size, 0
	.set _Z6mk_fwd4Args.uses_vcc, 1
	.set _Z6mk_fwd4Args.uses_flat_scratch, 0
	.set _Z6mk_fwd4Args.has_dyn_sized_stack, 0
	.set _Z6mk_fwd4Args.has_recursion, 0
	.set _Z6mk_fwd4Args.has_indirect_call, 0

amdhsa.kernels:
  - .agpr_count:     0
    .args:
      - .offset:         0
        .size:           200
        .value_kind:     by_value
      - .offset:         200
        .size:           4
        .value_kind:     hidden_block_count_x
      - .offset:         204
        .size:           4
        .value_kind:     hidden_block_count_y
      - .offset:         208
        .size:           4
        .value_kind:     hidden_block_count_z
      - .offset:         212
        .size:           2
        .value_kind:     hidden_group_size_x
      - .offset:         214
        .size:           2
        .value_kind:     hidden_group_size_y
      - .offset:         216
        .size:           2
        .value_kind:     hidden_group_size_z
      - .offset:         218
        .size:           2
        .value_kind:     hidden_remainder_x
      - .offset:         220
        .size:           2
        .value_kind:     hidden_remainder_y
      - .offset:         222
        .size:           2
        .value_kind:     hidden_remainder_z
      - .offset:         240
        .size:           8
        .value_kind:     hidden_global_offset_x
      - .offset:         248
        .size:           8
        .value_kind:     hidden_global_offset_y
      - .offset:         256
        .size:           8
        .value_kind:     hidden_global_offset_z
      - .offset:         264
        .size:           2
        .value_kind:     hidden_grid_dims
      - .offset:         288
        .size:           8
        .value_kind:     hidden_multigrid_sync_arg
      - .offset:         320
        .size:           4
        .value_kind:     hidden_dynamic_lds_size
    .group_segment_fixed_size: 0
    .kernarg_segment_align: 8
    .kernarg_segment_size: 456
    .language:       OpenCL C
    .language_version:
      - 2
      - 0
    .max_flat_workgroup_size: 512
    .name:           _Z6mk_fwd4Args
    .private_segment_fixed_size: 0
    .sgpr_count:     106
    .sgpr_spill_count: 2
    .symbol:         _Z6mk_fwd4Args.kd
    .uniform_work_group_size: 1
    .uses_dynamic_stack: false
    .vgpr_count:     256
    .vgpr_spill_count: 0
    .wavefront_size: 64
